# retstate k-step loads issued up front with counted waits (on top of XCD-barrier seam after phase A)
# speedup vs baseline: 1.1776x; 1.0307x over previous
.LBB0_27:
	v_lshl_add_u64 v[248:249], s[52:53], 0, v[10:11]
	v_lshl_add_u64 v[248:249], v[248:249], 0, s[0:1]
	global_load_dword v101, v[248:249], off
	global_load_dword v105, v[248:249], off offset:4
	v_lshl_add_u64 v[250:251], s[54:55], 0, v[10:11]
	v_lshl_add_u64 v[250:251], v[250:251], 0, s[0:1]
	global_load_dword v102, v[250:251], off
	global_load_dword v106, v[250:251], off offset:4
	v_lshl_add_u64 v[248:249], s[8:9], 0, v[4:5]
	v_lshl_add_u64 v[248:249], v[248:249], 0, v[12:13]
	global_load_dword v103, v[248:249], off
	global_load_dword v107, v[248:249], off offset:256
	v_lshl_add_u64 v[250:251], s[10:11], 0, v[4:5]
	v_lshl_add_u64 v[250:251], v[250:251], 0, v[12:13]
	global_load_dword v104, v[250:251], off
	global_load_dword v108, v[250:251], off offset:256
	s_waitcnt vmcnt(0)
	s_mov_b64 s[4:5], s[52:53]
	s_nop 0
	v_lshl_add_u64 v[14:15], s[4:5], 0, v[10:11]
	v_lshl_add_u64 v[14:15], v[14:15], 0, s[0:1]
	s_mov_b64 s[4:5], s[54:55]
	v_mov_b32_e32 v2, v101
	s_nop 0
	v_lshl_add_u64 v[14:15], s[4:5], 0, v[10:11]
	v_lshl_add_u64 v[14:15], v[14:15], 0, s[0:1]
	v_mov_b32_e32 v30, v102
	s_mov_b32 s4, 0xe2d4000
	v_mul_f32_e32 v14, v27, v30
	v_fma_f32 v14, v26, v2, -v14
	v_bfe_u32 v15, v14, 16, 1
	v_add3_u32 v31, v14, v15, s35
	v_lshl_add_u64 v[14:15], v[8:9], 0, v[4:5]
	v_add_co_u32_e32 v28, vcc, s4, v14
	v_mul_f32_e32 v14, v26, v30
	v_fmac_f32_e32 v14, v27, v2
	v_bfe_u32 v2, v14, 16, 1
	v_addc_co_u32_e32 v29, vcc, 0, v15, vcc
	v_add3_u32 v2, v14, v2, s35
	s_mov_b64 s[4:5], s[8:9]
	global_store_short_d16_hi v[28:29], v31, off
	global_store_short_d16_hi v[28:29], v2, off offset:2048
	v_lshl_add_u64 v[8:9], v[8:9], 0, 4
	v_lshl_add_u64 v[14:15], s[4:5], 0, v[4:5]
	v_lshl_add_u64 v[14:15], v[14:15], 0, v[12:13]
	v_mov_b32_e32 v2, v103
	s_mov_b32 s4, 0xe354000
	v_bfe_u32 v14, v2, 16, 1
	v_add3_u32 v2, v2, v14, s35
	v_lshl_add_u64 v[14:15], v[6:7], 0, v[4:5]
	v_add_co_u32_e32 v14, vcc, s4, v14
	s_mov_b64 s[4:5], s[10:11]
	s_nop 0
	v_addc_co_u32_e32 v15, vcc, 0, v15, vcc
	global_store_short_d16_hi v[14:15], v2, off
	v_lshl_add_u64 v[6:7], v[6:7], 0, s[96:97]
	v_lshl_add_u64 v[30:31], s[4:5], 0, v[4:5]
	v_lshl_add_u64 v[30:31], v[30:31], 0, v[12:13]
	v_mov_b32_e32 v2, v104
	s_mov_b64 s[4:5], s[52:53]
	v_xor_b32_e32 v2, 0x80000000, v2
	v_bfe_u32 v30, v2, 16, 1
	v_add3_u32 v2, v2, v30, s35
	global_store_short_d16_hi v[14:15], v2, off offset:128
	s_nop 0
	v_lshl_add_u64 v[30:31], s[4:5], 0, v[10:11]
	v_lshl_add_u64 v[30:31], v[30:31], 0, s[0:1]
	s_mov_b64 s[4:5], s[54:55]
	v_mov_b32_e32 v2, v105
	s_nop 0
	v_lshl_add_u64 v[30:31], s[4:5], 0, v[10:11]
	v_lshl_add_u64 v[30:31], v[30:31], 0, s[0:1]
	v_mov_b32_e32 v30, v106
	s_mov_b64 s[4:5], s[8:9]
	s_add_u32 s0, s0, 8
	s_addc_u32 s1, s1, 0
	s_cmp_eq_u32 s0, 64
	v_mul_f32_e32 v31, v27, v30
	v_mul_f32_e32 v30, v26, v30
	v_fma_f32 v31, v26, v2, -v31
	v_fmac_f32_e32 v30, v27, v2
	v_bfe_u32 v32, v31, 16, 1
	v_bfe_u32 v2, v30, 16, 1
	v_add3_u32 v31, v31, v32, s35
	v_add3_u32 v2, v30, v2, s35
	global_store_short_d16_hi v[28:29], v31, off offset:2
	global_store_short_d16_hi v[28:29], v2, off offset:2050
	s_nop 0
	v_lshl_add_u64 v[28:29], s[4:5], 0, v[4:5]
	v_lshl_add_u64 v[28:29], v[28:29], 0, v[12:13]
	v_mov_b32_e32 v2, v107
	s_mov_b64 s[4:5], s[10:11]
	v_bfe_u32 v28, v2, 16, 1
	v_add3_u32 v2, v2, v28, s35
	global_store_short_d16_hi v[14:15], v2, off offset:256
	s_nop 0
	v_lshl_add_u64 v[28:29], s[4:5], 0, v[4:5]
	v_lshl_add_u64 v[28:29], v[28:29], 0, v[12:13]
	v_mov_b32_e32 v2, v108
	v_lshl_add_u64 v[12:13], v[12:13], 0, s[96:97]
	v_xor_b32_e32 v2, 0x80000000, v2
	v_bfe_u32 v28, v2, 16, 1
	v_add3_u32 v2, v2, v28, s35
	global_store_short_d16_hi v[14:15], v2, off offset:384
	s_cbranch_scc0 .LBB0_27
	s_mov_b64 s[0:1], 0

.LBB0_698:
	s_mov_b64 s[0:1], exec

.LBB0_710:
	s_xor_b64 s[0:1], s[0:1], -1
	v_writelane_b32 v255, s0, 10
	s_lshl_b32 s20, s2, 10
	s_mov_b32 s21, s5
	v_writelane_b32 v255, s1, 11
	s_mul_i32 s0, s2, 5
	v_writelane_b32 v253, s0, 53
	s_mul_i32 s0, s2, 0x1800
	s_mov_b32 s1, s5
	v_writelane_b32 v253, s0, 50
	s_mul_i32 s58, s2, 0x140000
	s_nop 0
	v_writelane_b32 v253, s1, 51
	s_lshl_b32 s0, s2, 3
	s_mov_b32 s1, s5
	v_writelane_b32 v255, s0, 12
	s_nop 1
	v_writelane_b32 v255, s1, 13
	s_mul_i32 s0, s2, 0x4800
	v_writelane_b32 v255, s0, 14
	s_mul_i32 s0, s2, 0x600
	s_mov_b32 s1, s5
	v_writelane_b32 v255, s0, 15
	s_nop 1
	v_writelane_b32 v255, s1, 16
	s_lshl_b32 s0, s2, 6
	v_writelane_b32 v255, s0, 17
	s_lshl_b32 s0, s2, 1
	s_mov_b32 s1, s5
	v_writelane_b32 v255, s0, 18
	s_nop 1
	v_writelane_b32 v255, s1, 19
	s_lshl_b32 s0, s2, 9
	v_writelane_b32 v255, s0, 20
	s_mov_b32 s0, 1
	v_writelane_b32 v253, s0, 52
	v_writelane_b32 v253, s20, 55
	s_nop 1
	v_writelane_b32 v253, s21, 56
	s_cmp_lg_u32 s2, 0
	s_cbranch_scc1 .LBB0_713
	s_mov_b32 s0, 0
	v_writelane_b32 v253, s0, 52
	s_branch .Ltramp_bar0

.Ltramp_bar0:
	s_branch .LBB0_3310

.LBB0_1888:
	v_lshl_add_u64 v[224:225], v[82:83], 0, s[8:9]
	global_load_dwordx4 v[216:219], v[224:225], off
	v_lshl_add_u64 v[224:225], v[80:81], 0, s[8:9]
	global_load_dwordx4 v[220:223], v[224:225], off
	v_lshl_add_u64 v[226:227], v[2:3], 0, s[8:9]
	s_mov_b32 s98, 0x9a80000
	s_mov_b32 s99, 0
	v_lshl_add_u64 v[226:227], v[226:227], 0, s[98:99]
	s_mov_b64 s[98:99], 0x2000
	global_load_dwordx4 v[146:149], v[226:227], off
	v_lshl_add_u64 v[226:227], v[226:227], 0, s[98:99]
	global_load_dwordx4 v[150:153], v[226:227], off
	v_lshl_add_u64 v[226:227], v[226:227], 0, s[98:99]
	global_load_dwordx4 v[154:157], v[226:227], off
	v_lshl_add_u64 v[226:227], v[226:227], 0, s[98:99]
	global_load_dwordx4 v[158:161], v[226:227], off
	v_lshl_add_u64 v[226:227], v[226:227], 0, s[98:99]
	global_load_dwordx4 v[162:165], v[226:227], off
	v_lshl_add_u64 v[226:227], v[226:227], 0, s[98:99]
	global_load_dwordx4 v[166:169], v[226:227], off
	v_lshl_add_u64 v[226:227], v[226:227], 0, s[98:99]
	global_load_dwordx4 v[170:173], v[226:227], off
	v_lshl_add_u64 v[226:227], v[226:227], 0, s[98:99]
	global_load_dwordx4 v[174:177], v[226:227], off
	v_add_u32_e32 v72, -7, v91
	v_add_u32_e32 v73, 7, v92
	v_cndmask_b32_e32 v72, v72, v73, vcc
	v_cvt_f32_u32_e32 v72, v72
	v_add_u32_e32 v73, 6, v92
	s_mov_b32 s0, 0x9a80000
	v_mul_f32_e32 v72, v89, v72
	v_mul_f32_e32 v72, 0x3fb8aa3b, v72
	v_exp_f32_e32 v76, v72
	v_add_u32_e32 v72, -6, v91
	v_cndmask_b32_e32 v72, v72, v73, vcc
	v_cvt_f32_u32_e32 v72, v72
	v_add_u32_e32 v73, 5, v92
	v_mul_f32_e32 v72, v89, v72
	v_mul_f32_e32 v72, 0x3fb8aa3b, v72
	v_exp_f32_e32 v78, v72
	v_add_u32_e32 v72, -5, v91
	v_cndmask_b32_e32 v72, v72, v73, vcc
	v_cvt_f32_u32_e32 v72, v72
	v_add_u32_e32 v73, 4, v92
	v_mul_f32_e32 v72, v89, v72
	v_mul_f32_e32 v72, 0x3fb8aa3b, v72
	v_exp_f32_e32 v77, v72
	v_add_u32_e32 v72, -4, v91
	v_cndmask_b32_e32 v72, v72, v73, vcc
	v_cvt_f32_u32_e32 v72, v72
	v_add_u32_e32 v73, 3, v92
	v_mul_f32_e32 v72, v89, v72
	v_mul_f32_e32 v72, 0x3fb8aa3b, v72
	v_exp_f32_e32 v79, v72
	v_add_u32_e32 v72, -3, v91
	v_cndmask_b32_e32 v72, v72, v73, vcc
	v_cvt_f32_u32_e32 v72, v72
	v_add_u32_e32 v73, 2, v92
	v_mul_f32_e32 v72, v89, v72
	v_mul_f32_e32 v72, 0x3fb8aa3b, v72
	v_exp_f32_e32 v84, v72
	v_add_u32_e32 v72, -2, v91
	v_cndmask_b32_e32 v72, v72, v73, vcc
	v_cvt_f32_u32_e32 v72, v72
	v_add_u32_e32 v73, 1, v92
	v_mul_f32_e32 v72, v89, v72
	v_mul_f32_e32 v72, 0x3fb8aa3b, v72
	v_exp_f32_e32 v86, v72
	v_add_u32_e32 v72, -1, v91
	v_cndmask_b32_e32 v72, v72, v73, vcc
	v_cvt_f32_u32_e32 v72, v72
	v_mul_f32_e32 v72, v89, v72
	v_mul_f32_e32 v72, 0x3fb8aa3b, v72
	v_exp_f32_e32 v85, v72
	v_cndmask_b32_e32 v72, v91, v92, vcc
	v_cvt_f32_u32_e32 v72, v72
	v_add_u32_e32 v91, 32, v91
	v_subrev_u32_e32 v92, 32, v92
	v_mul_f32_e32 v72, v89, v72
	v_mul_f32_e32 v72, 0x3fb8aa3b, v72
	v_exp_f32_e32 v87, v72
	v_lshl_add_u64 v[72:73], v[82:83], 0, s[8:9]
	s_waitcnt vmcnt(9)
	v_mov_b32_e32 v72, v216
	v_mov_b32_e32 v73, v217
	v_mov_b32_e32 v74, v218
	v_mov_b32_e32 v75, v219
	v_lshlrev_b32_e32 v95, 16, v73
	v_lshlrev_b32_e32 v94, 16, v72
	v_and_b32_e32 v73, 0xffff0000, v73
	v_and_b32_e32 v72, 0xffff0000, v72
	v_lshlrev_b32_e32 v97, 16, v75
	v_lshlrev_b32_e32 v96, 16, v74
	v_and_b32_e32 v75, 0xffff0000, v75
	v_and_b32_e32 v74, 0xffff0000, v74
	v_pk_mul_f32 v[72:73], v[78:79], v[72:73]
	v_pk_mul_f32 v[74:75], v[86:87], v[74:75]
	v_pk_mul_f32 v[94:95], v[76:77], v[94:95]
	v_pk_mul_f32 v[96:97], v[84:85], v[96:97]
	v_bfe_u32 v98, v74, 16, 1
	v_bfe_u32 v99, v73, 16, 1
	v_bfe_u32 v93, v75, 16, 1
	v_bfe_u32 v100, v72, 16, 1
	v_add3_u32 v73, v73, v99, s34
	v_add3_u32 v74, v74, v98, s34
	v_bfe_u32 v98, v95, 16, 1
	v_bfe_u32 v99, v96, 16, 1
	v_add3_u32 v72, v72, v100, s34
	v_add3_u32 v75, v75, v93, s34
	v_bfe_u32 v93, v94, 16, 1
	v_bfe_u32 v100, v97, 16, 1
	v_add3_u32 v96, v96, v99, s34
	v_add3_u32 v95, v95, v98, s34
	v_add3_u32 v97, v97, v100, s34
	v_add3_u32 v93, v94, v93, s34
	v_lshrrev_b32_e32 v94, 16, v95
	v_lshrrev_b32_e32 v95, 16, v96
	v_lshrrev_b32_e32 v96, 16, v97
	v_and_or_b32 v74, v74, s28, v95
	v_and_or_b32 v73, v73, s28, v94
	v_lshl_add_u64 v[94:95], v[80:81], 0, s[8:9]
	v_and_or_b32 v75, v75, s28, v96
	s_waitcnt vmcnt(8)
	v_mov_b32_e32 v94, v220
	v_mov_b32_e32 v95, v221
	v_mov_b32_e32 v96, v222
	v_mov_b32_e32 v97, v223
	v_lshrrev_b32_e32 v93, 16, v93
	v_and_or_b32 v72, v72, s28, v93
	v_lshlrev_b32_e32 v99, 16, v95
	v_lshlrev_b32_e32 v98, 16, v94
	v_and_b32_e32 v95, 0xffff0000, v95
	v_and_b32_e32 v94, 0xffff0000, v94
	v_pk_mul_f32 v[78:79], v[78:79], v[94:95]
	v_lshlrev_b32_e32 v95, 16, v97
	v_lshlrev_b32_e32 v94, 16, v96
	v_pk_mul_f32 v[84:85], v[84:85], v[94:95]
	v_and_b32_e32 v95, 0xffff0000, v97
	v_and_b32_e32 v94, 0xffff0000, v96
	v_pk_mul_f32 v[86:87], v[86:87], v[94:95]
	v_bfe_u32 v95, v79, 16, 1
	v_bfe_u32 v93, v87, 16, 1
	v_bfe_u32 v94, v86, 16, 1
	v_bfe_u32 v96, v78, 16, 1
	v_add3_u32 v96, v78, v96, s34
	v_add3_u32 v95, v79, v95, s34
	v_add3_u32 v78, v86, v94, s34
	v_add3_u32 v79, v87, v93, s34
	v_bfe_u32 v93, v84, 16, 1
	v_bfe_u32 v94, v85, 16, 1
	v_add3_u32 v85, v85, v94, s34
	v_add3_u32 v84, v84, v93, s34
	v_pk_mul_f32 v[76:77], v[76:77], v[98:99]
	v_lshrrev_b32_e32 v84, 16, v84
	v_lshrrev_b32_e32 v85, 16, v85
	v_bfe_u32 v86, v76, 16, 1
	v_bfe_u32 v87, v77, 16, 1
	v_and_or_b32 v79, v79, s28, v85
	v_and_or_b32 v78, v78, s28, v84
	v_lshl_add_u64 v[84:85], v[2:3], 0, s[8:9]
	v_add3_u32 v77, v77, v87, s34
	v_add3_u32 v76, v76, v86, s34
	v_add_co_u32_e64 v86, s[0:1], s0, v84
	v_lshrrev_b32_e32 v76, 16, v76
	v_lshrrev_b32_e32 v77, 16, v77
	v_addc_co_u32_e64 v87, s[0:1], 0, v85, s[0:1]
	v_and_or_b32 v77, v95, s28, v77
	v_and_or_b32 v76, v96, s28, v76
	s_waitcnt vmcnt(7)
	s_mov_b32 s0, 0x9a82000
	v_add_co_u32_e64 v86, s[0:1], s0, v84
	s_add_u32 s8, s8, 64
	s_nop 0
	v_addc_co_u32_e64 v87, s[0:1], 0, v85, s[0:1]
	s_mov_b32 s0, 0x9a84000
	s_addc_u32 s9, s9, 0
	s_cmpk_lg_i32 s8, 0x200
	v_mfma_f32_16x16x32_bf16 v[68:71], v[72:75], v[146:149], v[68:71]
	v_mfma_f32_16x16x32_bf16 v[28:31], v[76:79], v[146:149], v[28:31]
	s_waitcnt vmcnt(6)
	v_add_co_u32_e64 v86, s[0:1], s0, v84
	v_mfma_f32_16x16x32_bf16 v[64:67], v[72:75], v[150:153], v[64:67]
	v_addc_co_u32_e64 v87, s[0:1], 0, v85, s[0:1]
	s_mov_b32 s0, 0x9a86000
	v_mfma_f32_16x16x32_bf16 v[24:27], v[76:79], v[150:153], v[24:27]
	s_waitcnt vmcnt(5)
	v_add_co_u32_e64 v86, s[0:1], s0, v84
	v_mfma_f32_16x16x32_bf16 v[60:63], v[72:75], v[154:157], v[60:63]
	v_addc_co_u32_e64 v87, s[0:1], 0, v85, s[0:1]
	s_mov_b32 s0, 0x9a88000
	v_mfma_f32_16x16x32_bf16 v[20:23], v[76:79], v[154:157], v[20:23]
	s_waitcnt vmcnt(4)
	v_add_co_u32_e64 v86, s[0:1], s0, v84
	v_mfma_f32_16x16x32_bf16 v[56:59], v[72:75], v[158:161], v[56:59]
	v_addc_co_u32_e64 v87, s[0:1], 0, v85, s[0:1]
	s_mov_b32 s0, 0x9a8a000
	v_mfma_f32_16x16x32_bf16 v[16:19], v[76:79], v[158:161], v[16:19]
	s_waitcnt vmcnt(3)
	v_add_co_u32_e64 v86, s[0:1], s0, v84
	v_mfma_f32_16x16x32_bf16 v[52:55], v[72:75], v[162:165], v[52:55]
	v_addc_co_u32_e64 v87, s[0:1], 0, v85, s[0:1]
	s_mov_b32 s0, 0x9a8c000
	v_mfma_f32_16x16x32_bf16 v[12:15], v[76:79], v[162:165], v[12:15]
	s_waitcnt vmcnt(2)
	v_add_co_u32_e64 v86, s[0:1], s0, v84
	v_mfma_f32_16x16x32_bf16 v[48:51], v[72:75], v[166:169], v[48:51]
	v_addc_co_u32_e64 v87, s[0:1], 0, v85, s[0:1]
	s_mov_b32 s0, 0x9a8e000
	s_nop 0
	v_add_co_u32_e64 v84, s[0:1], s0, v84
	v_mfma_f32_16x16x32_bf16 v[8:11], v[76:79], v[166:169], v[8:11]
	s_nop 0
	v_addc_co_u32_e64 v85, s[0:1], 0, v85, s[0:1]
	s_waitcnt vmcnt(1)
	v_mfma_f32_16x16x32_bf16 v[44:47], v[72:75], v[170:173], v[44:47]
	s_waitcnt vmcnt(0)
	v_mfma_f32_16x16x32_bf16 v[32:35], v[76:79], v[170:173], v[32:35]
	v_mfma_f32_16x16x32_bf16 v[40:43], v[72:75], v[174:177], v[40:43]
	v_mfma_f32_16x16x32_bf16 v[36:39], v[76:79], v[174:177], v[36:39]
	s_cbranch_scc1 .LBB0_1888
	s_ashr_i32 s3, s2, 31
	s_lshl_b64 s[2:3], s[2:3], 2
	v_readlane_b32 s8, v255, 18
	s_or_b32 s2, s2, s15
	v_readlane_b32 s9, v255, 19
	s_mov_b64 s[0:1], s[60:61]
	s_or_b64 s[2:3], s[2:3], s[8:9]
	s_lshl_b64 s[2:3], s[2:3], 18
	s_add_u32 s0, s0, s2
	s_addc_u32 s1, s1, s3
	s_lshl_b32 s2, s14, 16
	s_add_u32 s0, s0, s2
	s_addc_u32 s1, s1, 0
	v_lshl_or_b32 v2, v88, 2, v90
	v_lshlrev_b32_e32 v0, 2, v0
	v_lshl_add_u64 v[72:73], s[0:1], 0, v[0:1]
	s_mov_b64 s[0:1], 0x3200000
	v_ashrrev_i32_e32 v3, 31, v2
	v_or_b32_e32 v76, 1, v2
	v_lshl_add_u64 v[72:73], v[72:73], 0, s[0:1]
	v_lshlrev_b64 v[74:75], 9, v[2:3]
	v_ashrrev_i32_e32 v77, 31, v76
	v_lshl_add_u64 v[74:75], v[72:73], 0, v[74:75]
	v_lshlrev_b64 v[76:77], 9, v[76:77]
	global_store_dword v[74:75], v68, off
	v_lshl_add_u64 v[76:77], v[72:73], 0, v[76:77]
	v_or_b32_e32 v68, 2, v2
	v_or_b32_e32 v78, 3, v2
	global_store_dword v[76:77], v69, off
	v_ashrrev_i32_e32 v69, 31, v68
	v_ashrrev_i32_e32 v79, 31, v78
	v_lshlrev_b64 v[68:69], 9, v[68:69]
	v_lshlrev_b64 v[78:79], 9, v[78:79]
	v_lshl_add_u64 v[68:69], v[72:73], 0, v[68:69]
	v_lshl_add_u64 v[78:79], v[72:73], 0, v[78:79]
	global_store_dword v[68:69], v70, off
	global_store_dword v[78:79], v71, off
	global_store_dword v[74:75], v64, off offset:64
	global_store_dword v[76:77], v65, off offset:64
	global_store_dword v[68:69], v66, off offset:64
	global_store_dword v[78:79], v67, off offset:64
	global_store_dword v[74:75], v60, off offset:128
	global_store_dword v[76:77], v61, off offset:128
	global_store_dword v[68:69], v62, off offset:128
	global_store_dword v[78:79], v63, off offset:128
	global_store_dword v[74:75], v56, off offset:192
	global_store_dword v[76:77], v57, off offset:192
	global_store_dword v[68:69], v58, off offset:192
	global_store_dword v[78:79], v59, off offset:192
	global_store_dword v[74:75], v52, off offset:256
	global_store_dword v[76:77], v53, off offset:256
	global_store_dword v[68:69], v54, off offset:256
	global_store_dword v[78:79], v55, off offset:256
	global_store_dword v[74:75], v48, off offset:320
	global_store_dword v[76:77], v49, off offset:320
	global_store_dword v[68:69], v50, off offset:320
	global_store_dword v[78:79], v51, off offset:320
	global_store_dword v[74:75], v44, off offset:384
	global_store_dword v[76:77], v45, off offset:384
	global_store_dword v[68:69], v46, off offset:384
	global_store_dword v[78:79], v47, off offset:384
	global_store_dword v[74:75], v40, off offset:448
	global_store_dword v[76:77], v41, off offset:448
	global_store_dword v[68:69], v42, off offset:448
	global_store_dword v[78:79], v43, off offset:448
	v_or_b32_e32 v40, 16, v2
	v_ashrrev_i32_e32 v41, 31, v40
	v_or_b32_e32 v42, 17, v2
	v_lshlrev_b64 v[40:41], 9, v[40:41]
	v_ashrrev_i32_e32 v43, 31, v42
	v_lshl_add_u64 v[40:41], v[72:73], 0, v[40:41]
	v_lshlrev_b64 v[42:43], 9, v[42:43]
	global_store_dword v[40:41], v28, off
	v_lshl_add_u64 v[42:43], v[72:73], 0, v[42:43]
	v_or_b32_e32 v28, 18, v2
	v_or_b32_e32 v2, 19, v2
	global_store_dword v[42:43], v29, off
	v_ashrrev_i32_e32 v29, 31, v28
	v_ashrrev_i32_e32 v3, 31, v2
	v_lshlrev_b64 v[28:29], 9, v[28:29]
	v_lshlrev_b64 v[2:3], 9, v[2:3]
	v_lshl_add_u64 v[28:29], v[72:73], 0, v[28:29]
	v_lshl_add_u64 v[2:3], v[72:73], 0, v[2:3]
	s_mov_b64 s[0:1], 0
	global_store_dword v[28:29], v30, off
	global_store_dword v[2:3], v31, off
	global_store_dword v[40:41], v24, off offset:64
	global_store_dword v[42:43], v25, off offset:64
	global_store_dword v[28:29], v26, off offset:64
	global_store_dword v[2:3], v27, off offset:64
	global_store_dword v[40:41], v20, off offset:128
	global_store_dword v[42:43], v21, off offset:128
	global_store_dword v[28:29], v22, off offset:128
	global_store_dword v[2:3], v23, off offset:128
	global_store_dword v[40:41], v16, off offset:192
	global_store_dword v[42:43], v17, off offset:192
	global_store_dword v[28:29], v18, off offset:192
	global_store_dword v[2:3], v19, off offset:192
	global_store_dword v[40:41], v12, off offset:256
	global_store_dword v[42:43], v13, off offset:256
	global_store_dword v[28:29], v14, off offset:256
	global_store_dword v[2:3], v15, off offset:256
	global_store_dword v[40:41], v8, off offset:320
	global_store_dword v[42:43], v9, off offset:320
	global_store_dword v[28:29], v10, off offset:320
	global_store_dword v[2:3], v11, off offset:320
	global_store_dword v[40:41], v32, off offset:384
	global_store_dword v[42:43], v33, off offset:384
	global_store_dword v[28:29], v34, off offset:384
	global_store_dword v[2:3], v35, off offset:384
	global_store_dword v[40:41], v36, off offset:448
	global_store_dword v[42:43], v37, off offset:448
	global_store_dword v[28:29], v38, off offset:448
	global_store_dword v[2:3], v39, off offset:448
	s_branch .LBB0_1881
